# attention tile loop: K reads before DMA issue, DMA addresses from SGPR bases, skip accumulator-init movs when bias class unchanged, drop phi-copy movs
# speedup vs baseline: 1.0401x; 1.0349x over previous
; __device__ __forceinline__ void attn_unit(LAS unsigned char* lds, const bf16_t* __restrict__ U3, const bf16_t* __restrict__ VT, bf16_t* __restrict__ MIX, ...
;     ...
;     bf16x8 qr[4];
;     { const bf16_t* qp = U3 + (size_t)(rowbase + q - NMETA) * 1536 + h * 128 + c * 64 + hi * 8;
; #pragma unroll
;       for (int d0 = 0; d0 < 4; ++d0) qr[d0] = *(const bf16x8*)(qp + d0 * 16); }
;     const bf16_t* kg[2]; const bf16_t* vg[2];
; #pragma unroll
;     for (int i = 0; i < 2; ++i) { const int row = 4 * (i * 8 + w) + (lane >> 4), kch = (lane & 15) ^ (row & 15);
;         kg[i] = U3 + (size_t)row * 1536 + 512 + h * 128 + kch * 8;
;         const int rp = row, p = (lane & 15) ^ (rp & 15), dv = 2 * rp + (p >> 3), ch = p & 7;
;         vg[i] = VT + (size_t)(h * 128 + dv) * MPAD + ch * 8; }
;     ...
;     const int pi = (r32 & 0x13) | ((r32 & 4) << 1) | ((r32 & 8) >> 1);
;     unsigned koff[4], voff[4];
; #pragma unroll
;     for (int d0 = 0; d0 < 4; ++d0) koff[d0] = pi * 256 + (((c * 8 + d0 * 2 + hi) ^ (pi & 15)) << 4);
; #pragma unroll
;     for (int j = 0; j < 4; ++j) voff[j] = 16384 + (r32 >> 1) * 256 + (((((r32 & 1) << 3) + 2 * j + hi) ^ (r32 >> 1)) << 4);
;     ATT_DMA(0, 0); ATT_DMA(1, 1);
;     asm volatile("s_waitcnt vmcnt(4)" ::: "memory");
;     asm volatile("s_waitcnt lgkmcnt(0)" ::: "memory"); __builtin_amdgcn_s_barrier(); asm volatile("" ::: "memory");
;     const float bL = lut[0], bR = lut[256];
;     f32x16 o[4];
; #pragma unroll
;     for (int d0 = 0; d0 < 4; ++d0)
; #pragma unroll
;         for (int r = 0; r < 16; ++r) o[d0][r] = 0.f;
;     float mhat = 0.f, l = 0.f;
;     bf16x8 pf[4];
; #pragma unroll
;     for (int j = 0; j < 4; ++j) pf[j] = (bf16x8){0, 0, 0, 0, 0, 0, 0, 0};
;     int slot = 0, slotp = 0, slot2 = 2;
.LBB0_513:
	s_or_b64 exec, exec, s[12:13]
	s_lshl_b32 s12, s17, 13
	s_ashr_i32 s14, s73, 6
	s_ashr_i32 s74, s73, 8
	s_add_i32 s12, s12, 0x8000
	s_lshl_b32 s13, s17, 11
	s_and_b64 s[10:11], exec, s[10:11]
	s_cselect_b32 s10, s13, s12
	s_and_b32 s72, s14, 3
	s_lshl_b32 s11, s16, 7
	s_lshl_b32 s12, s72, 5
	s_or_b32 s76, s12, s11
	v_and_b32_e32 v158, 31, v155
	s_or_b32 s62, s76, 16
	v_add_u32_e32 v168, s62, v158
	s_add_i32 s63, s10, -16
	v_add_u32_e32 v2, s63, v168
	v_mov_b64_e32 v[0:1], s[20:21]
	v_mad_i64_i32 v[2:3], s[12:13], v2, s69, v[0:1]
	s_lshl_b32 s12, s74, 6
	v_bfe_u32 v159, v155, 5, 1
	s_ashr_i32 s13, s12, 31
	s_lshl_b32 s11, s14, 2
	v_bfe_u32 v156, v155, 4, 2
	v_lshl_add_u64 v[2:3], s[12:13], 1, v[2:3]
	v_lshlrev_b32_e32 v160, 4, v159
	v_or_b32_e32 v8, s11, v156
	v_lshl_add_u64 v[2:3], v[2:3], 0, v[160:161]
	v_bitop3_b32 v4, v8, 15, v155 bitop3:0x48
	global_load_dwordx4 v[112:115], v[2:3], off
	global_load_dwordx4 v[116:119], v[2:3], off offset:32
	global_load_dwordx4 v[120:123], v[2:3], off offset:64
	global_load_dwordx4 v[124:127], v[2:3], off offset:96
	v_bitop3_b32 v6, s11, v155, v156 bitop3:0x36
	v_mad_i64_i32 v[2:3], s[12:13], v8, s69, v[0:1]
	v_lshlrev_b32_e32 v4, 4, v4
	v_mov_b32_e32 v5, v161
	v_lshl_add_u64 v[146:147], v[2:3], 0, v[4:5]
	v_bfe_u32 v2, v6, 3, 1
	v_lshl_add_u32 v3, v8, 1, s37
	v_or_b32_e32 v4, v2, v3
	v_mov_b64_e32 v[2:3], s[52:53]
	v_lshlrev_b32_e32 v6, 4, v6
	v_mad_i64_i32 v[4:5], s[12:13], v4, s41, v[2:3]
	v_and_b32_e32 v6, 0x70, v6
	v_mov_b32_e32 v7, v161
	v_lshl_add_u64 v[148:149], v[4:5], 0, v[6:7]
	v_add_u32_e32 v6, 32, v8
	v_bitop3_b32 v4, v6, 15, v155 bitop3:0x48
	v_xor_b32_e32 v7, v6, v155
	v_mad_i64_i32 v[0:1], s[12:13], v6, s69, v[0:1]
	v_lshlrev_b32_e32 v4, 4, v4
	v_mov_b32_e32 v5, v161
	v_lshl_add_u64 v[150:151], v[0:1], 0, v[4:5]
	v_bfe_u32 v0, v7, 3, 1
	v_lshl_add_u32 v1, v6, 1, s37
	v_or_b32_e32 v0, v0, v1
	v_mad_i64_i32 v[0:1], s[12:13], v0, s41, v[2:3]
	v_lshlrev_b32_e32 v2, 4, v7
	v_and_b32_e32 v2, 0x70, v2
	v_mov_b32_e32 v3, v161
	s_lshl_b32 s11, s14, 10
	v_lshl_add_u64 v[152:153], v[0:1], 0, v[2:3]
	s_add_i32 s77, s11, 0
	v_mad_i64_i32 v[0:1], s[12:13], s10, v212, v[146:147]
	v_lshl_add_u64 v[0:1], v[0:1], 0, s[86:87]
	s_mov_b32 m0, s77
	s_ashr_i32 s11, s10, 31
	global_load_lds_dwordx4 v[0:1], off
	v_mad_i64_i32 v[0:1], s[12:13], s10, v212, v[150:151]
	v_lshl_add_u64 v[0:1], v[0:1], 0, s[86:87]
	s_add_i32 m0, s77, 0x2000
	s_lshl_b64 s[12:13], s[10:11], 1
	global_load_lds_dwordx4 v[0:1], off
	v_lshl_add_u64 v[0:1], v[148:149], 0, s[12:13]
	s_add_i32 m0, s77, 0x4000
	s_or_b32 s11, s10, 64
	global_load_lds_dwordx4 v[0:1], off
	v_lshl_add_u64 v[2:3], v[152:153], 0, s[12:13]
	s_add_i32 m0, s77, 0x6000
	v_mad_i64_i32 v[4:5], s[12:13], s11, v212, v[146:147]
	global_load_lds_dwordx4 v[2:3], off
	s_add_i32 m0, s77, 0x8000
	v_lshl_add_u64 v[4:5], v[4:5], 0, s[86:87]
	global_load_lds_dwordx4 v[4:5], off
	v_mad_i64_i32 v[4:5], s[12:13], s11, v212, v[150:151]
	v_lshl_add_u64 v[4:5], v[4:5], 0, s[86:87]
	s_add_i32 m0, s77, 0xa000
	v_lshl_add_u64 v[0:1], v[0:1], 0, s[90:91]
	global_load_lds_dwordx4 v[4:5], off
	s_add_i32 m0, s77, 0xc000
	s_add_i32 s79, 0, 0x20000
	global_load_lds_dwordx4 v[0:1], off
	v_lshl_add_u64 v[0:1], v[2:3], 0, s[90:91]
	s_add_i32 m0, s77, 0xe000
	v_lshl_or_b32 v3, s74, 3, v159
	global_load_lds_dwordx4 v[0:1], off
	v_subrev_u32_e32 v146, s20, v146
	v_subrev_u32_e32 v150, s20, v150
	v_subrev_u32_e32 v148, s52, v148
	v_subrev_u32_e32 v152, s52, v152
	v_and_b32_e32 v0, 19, v155
	v_lshlrev_b32_e32 v1, 1, v155
	v_and_or_b32 v0, v1, 8, v0
	v_lshrrev_b32_e32 v1, 1, v155
	v_and_b32_e32 v1, 4, v1
	v_or_b32_e32 v2, v0, v1
	v_bitop3_b32 v0, v0, 15, v1 bitop3:0xc8
	v_bitop3_b32 v1, v2, v3, 15 bitop3:0x6c
	v_lshlrev_b32_e32 v171, 8, v2
	v_lshlrev_b32_e32 v173, 4, v1
	v_bitop3_b32 v1, v3, v0, 2 bitop3:0x36
	v_lshlrev_b32_e32 v2, 3, v155
	v_lshlrev_b32_e32 v174, 4, v1
	v_bitop3_b32 v1, v3, v0, 4 bitop3:0x36
	v_bitop3_b32 v0, v3, v0, 6 bitop3:0x36
	v_and_b32_e32 v2, 8, v2
	v_lshlrev_b32_e32 v176, 4, v0
	v_bfe_u32 v0, v155, 1, 4
	v_or_b32_e32 v3, v2, v159
	s_waitcnt vmcnt(4)
	v_lshlrev_b32_e32 v175, 4, v1
	v_lshlrev_b32_e32 v1, 8, v0
	v_bitop3_b32 v2, v2, v0, v159 bitop3:0x36
	v_bitop3_b32 v4, v3, v0, 2 bitop3:0x36
	v_bitop3_b32 v5, v3, v0, 4 bitop3:0x36
	v_bitop3_b32 v0, v3, v0, 6 bitop3:0x36
	s_waitcnt lgkmcnt(0)
	s_barrier
	v_mov_b32_e32 v3, s79
	v_mov_b32_e32 v6, s50
	ds_read_b32 v178, v3 offset:640
	ds_read_b32 v180, v6 offset:640
	v_mov_b32_e32 v48, v161
	v_mov_b32_e32 v49, v161
	v_mov_b32_e32 v140, v161
	v_mov_b32_e32 v141, v161
	v_lshl_or_b32 v179, v2, 4, v1
	v_lshl_or_b32 v177, v4, 4, v1
	v_lshl_or_b32 v172, v5, 4, v1
	v_lshl_or_b32 v170, v0, 4, v1
	s_lshl_b32 s85, s75, 6
	v_mov_b32_e32 v50, v161
	v_mov_b32_e32 v51, v161
	v_mov_b32_e32 v52, v161
	v_mov_b32_e32 v53, v161
	v_mov_b32_e32 v54, v161
	v_mov_b32_e32 v55, v161
	v_mov_b32_e32 v56, v161
	v_mov_b32_e32 v57, v161
	v_mov_b32_e32 v58, v161
	v_mov_b32_e32 v59, v161
	v_mov_b32_e32 v60, v161
	v_mov_b32_e32 v61, v161
	v_mov_b32_e32 v62, v161
	v_mov_b32_e32 v63, v161
	v_mov_b32_e32 v142, v161
	v_mov_b32_e32 v143, v161
	v_mov_b64_e32 v[136:137], v[140:141]
	v_mov_b64_e32 v[132:133], v[140:141]
	v_mov_b64_e32 v[128:129], v[140:141]
	v_mov_b64_e32 v[32:33], v[48:49]
	v_mov_b64_e32 v[16:17], v[48:49]
	v_mov_b64_e32 v[0:1], v[48:49]
	v_lshlrev_b32_e32 v157, 3, v159
	s_mov_b32 s78, 2
	s_or_b32 s84, s10, 0x80
	s_add_i32 s97, s85, 64
	s_mov_b32 s33, 0
	v_mov_b32_e32 v169, 0
	v_mov_b64_e32 v[138:139], v[142:143]
	v_mov_b64_e32 v[134:135], v[142:143]
	v_mov_b64_e32 v[130:131], v[142:143]
	v_mov_b64_e32 v[34:35], v[50:51]
	v_mov_b64_e32 v[36:37], v[52:53]
	v_mov_b64_e32 v[38:39], v[54:55]
	v_mov_b64_e32 v[40:41], v[56:57]
	v_mov_b64_e32 v[42:43], v[58:59]
	v_mov_b64_e32 v[44:45], v[60:61]
	v_mov_b64_e32 v[46:47], v[62:63]
	v_mov_b64_e32 v[18:19], v[50:51]
	v_mov_b64_e32 v[20:21], v[52:53]
	v_mov_b64_e32 v[22:23], v[54:55]
	v_mov_b64_e32 v[24:25], v[56:57]
	v_mov_b64_e32 v[26:27], v[58:59]
	v_mov_b64_e32 v[28:29], v[60:61]
	v_mov_b64_e32 v[30:31], v[62:63]
	v_mov_b64_e32 v[2:3], v[50:51]
	v_mov_b64_e32 v[4:5], v[52:53]
	v_mov_b64_e32 v[6:7], v[54:55]
	v_mov_b64_e32 v[8:9], v[56:57]
	v_mov_b64_e32 v[10:11], v[58:59]
	v_mov_b64_e32 v[12:13], v[60:61]
	v_mov_b64_e32 v[14:15], v[62:63]
	v_mov_b32_e32 v181, 0
	s_mov_b32 s10, 0
	s_mov_b32 s16, 0
	s_mov_b32 s45, 2
	s_mov_b32 s99, -1
	s_waitcnt vmcnt(0) lgkmcnt(0)
; #define LAS __attribute__((address_space(3)))
; __device__ __forceinline__ void attn_unit(LAS unsigned char* lds, const bf16_t* __restrict__ U3, const bf16_t* __restrict__ VT, bf16_t* __restrict__ MIX, ...
;     ...
; #pragma unroll 1
;     for (int t = 0; t < NT; ++t) {
;         const bool mt = (t == NT - 1); const int k0 = mt ? 0 : NMETA + t * 64; LAS unsigned char* buf = lds + slot * STAGE; LAS unsigned char* pbuf = lds + slotp * STAGE;
;         const bool ahead = t + 2 < NT;
;         if (ahead) ATT_DMA(t + 2, slot2);
;         const int relmax = k0 + 63 - qw0, relmin = k0 - (qw0 + 31);
;         const bool farl = relmax <= -91, farr = relmin >= 91;
;         const bool slow = !(farl || farr) || mt;
;         f32x16 p0, p1;
;         ATT_SCORES();
.LBB0_514:
	s_cmp_le_u32 s78, s75
	s_mov_b32 s81, s10
	s_cselect_b64 s[24:25], -1, 0
	s_lshl_b32 s12, s81, 15
	s_add_i32 s43, s12, 0
	v_add3_u32 v182, s43, v173, v171
	v_add3_u32 v183, s43, v174, v171
	v_add3_u32 v184, s43, v175, v171
	v_add3_u32 v185, s43, v176, v171
	ds_read_b128 v[96:99], v182
	ds_read_b128 v[186:189], v182 offset:8192
	ds_read_b128 v[190:193], v183
	ds_read_b128 v[194:197], v183 offset:8192
	ds_read_b128 v[198:201], v184
	ds_read_b128 v[218:221], v184 offset:8192
	ds_read_b128 v[222:225], v185
	ds_read_b128 v[226:229], v185 offset:8192
	s_cmp_gt_u32 s78, s75
	s_cbranch_scc1 .LBB0_516
	s_lshl_b32 s10, s45, 15
	s_add_i32 s14, s77, s10
	s_add_i32 s10, s84, s33
	s_cmp_lt_u32 s78, s75
	s_cselect_b32 s10, s10, 0x18000
	s_mul_i32 s11, s10, 0xc00
	s_add_i32 s11, s11, 0x400
	s_add_u32 s100, s20, s11
	s_addc_u32 s101, s21, 0
	s_mov_b32 m0, s14
	s_lshl_b32 s11, s10, 1
	global_load_lds_dwordx4 v146, s[100:101]
	s_add_i32 m0, s14, 0x2000
	s_nop 0
	global_load_lds_dwordx4 v150, s[100:101]
	s_add_u32 s100, s52, s11
	s_addc_u32 s101, s53, 0
	s_add_i32 m0, s14, 0x4000
	s_nop 0
	global_load_lds_dwordx4 v148, s[100:101]
	s_add_i32 m0, s14, 0x6000
	s_nop 0
	global_load_lds_dwordx4 v152, s[100:101]
.LBB0_516:
	s_add_i32 s14, s33, 16
	s_cmp_eq_u32 s85, s33
	s_cselect_b64 s[10:11], -1, 0
	s_and_b64 s[12:13], s[10:11], exec
	s_cselect_b32 s56, 0, s14
	s_sub_i32 s12, s56, s62
	s_sub_i32 s13, s56, s76
	s_add_i32 s12, s12, 63
	s_sub_i32 s13, s13, 47
	s_cmpk_gt_i32 s12, 0xffa5
	s_cselect_b64 vcc, -1, 0
	s_cselect_b32 s14, 1, 0
	s_cmpk_lt_i32 s13, 0x5b
	s_cselect_b64 s[12:13], -1, 0
	s_and_b64 s[12:13], vcc, s[12:13]
	s_or_b64 s[12:13], s[10:11], s[12:13]
	s_cmp_lg_u64 s[12:13], 0
	s_cselect_b32 s14, 2, s14
	s_cmp_eq_u32 s14, s99
	s_cbranch_scc1 .Latt_skipinit
	s_mov_b32 s99, s14
	v_cndmask_b32_e32 v64, v178, v180, vcc
	v_cndmask_b32_e64 v64, v64, 0, s[12:13]
	v_sub_f32_e32 v80, v64, v181
	v_mov_b32_e32 v81, v80
	v_mov_b32_e32 v82, v80
	v_mov_b32_e32 v83, v80
	v_mov_b32_e32 v84, v80
	v_mov_b32_e32 v85, v80
	v_mov_b32_e32 v86, v80
	v_mov_b32_e32 v87, v80
	v_mov_b32_e32 v88, v80
	v_mov_b32_e32 v89, v80
	v_mov_b32_e32 v90, v80
	v_mov_b32_e32 v91, v80
	v_mov_b32_e32 v92, v80
	v_mov_b32_e32 v93, v80
	v_mov_b32_e32 v94, v80
	v_mov_b32_e32 v95, v80
.Latt_skipinit:
	s_setprio 1
	s_waitcnt lgkmcnt(0)
	v_mfma_f32_32x32x16_bf16 v[64:79], v[96:99], v[112:115], v[80:95]
	v_mfma_f32_32x32x16_bf16 v[96:111], v[186:189], v[112:115], v[80:95]
	v_mfma_f32_32x32x16_bf16 v[64:79], v[190:193], v[116:119], v[64:79]
	v_mfma_f32_32x32x16_bf16 v[96:111], v[194:197], v[116:119], v[96:111]
	v_mfma_f32_32x32x16_bf16 v[64:79], v[198:201], v[120:123], v[64:79]
	v_mfma_f32_32x32x16_bf16 v[96:111], v[218:221], v[120:123], v[96:111]
	v_mfma_f32_32x32x16_bf16 v[64:79], v[222:225], v[124:127], v[64:79]
	v_mfma_f32_32x32x16_bf16 v[96:111], v[226:229], v[124:127], v[96:111]
	s_setprio 0
	s_not_b64 s[14:15], s[12:13]
	s_andn2_b64 vcc, exec, s[12:13]
	s_cbranch_vccnz .LBB0_518
	v_or_b32_e32 v186, s56, v157
	v_sub_u32_e32 v186, v186, v168
	v_max_i32_e32 v186, 0xfffffee0, v186
	v_min_i32_e32 v186, 0xa8, v186
	s_add_i32 s98, s79, 0x480
	v_lshl_add_u32 v186, v186, 2, s98
	s_and_b64 vcc, exec, s[10:11]
	s_cbranch_vccnz .Latt_slow_mt_a
	ds_read2_b32 v[234:235], v186 offset1:1
	ds_read2_b32 v[236:237], v186 offset0:2 offset1:3
	ds_read2_b32 v[238:239], v186 offset0:4 offset1:5
	ds_read2_b32 v[240:241], v186 offset0:6 offset1:7
	ds_read2_b32 v[242:243], v186 offset0:16 offset1:17
	ds_read2_b32 v[244:245], v186 offset0:18 offset1:19
	ds_read2_b32 v[246:247], v186 offset0:20 offset1:21
	ds_read2_b32 v[248:249], v186 offset0:22 offset1:23
	ds_read2_b32 v[250:251], v186 offset0:32 offset1:33
	ds_read2_b32 v[252:253], v186 offset0:34 offset1:35
	ds_read2_b32 v[188:189], v186 offset0:36 offset1:37
	ds_read2_b32 v[190:191], v186 offset0:38 offset1:39
	ds_read2_b32 v[192:193], v186 offset0:48 offset1:49
	ds_read2_b32 v[194:195], v186 offset0:50 offset1:51
	ds_read2_b32 v[196:197], v186 offset0:52 offset1:53
	ds_read2_b32 v[198:199], v186 offset0:54 offset1:55
	s_waitcnt lgkmcnt(0)
	v_add_f32_e32 v64, v64, v234
	v_add_f32_e32 v65, v65, v235
	v_add_f32_e32 v66, v66, v236
	v_add_f32_e32 v67, v67, v237
	v_add_f32_e32 v68, v68, v238
	v_add_f32_e32 v69, v69, v239
	v_add_f32_e32 v70, v70, v240
	v_add_f32_e32 v71, v71, v241
	v_add_f32_e32 v72, v72, v242
	v_add_f32_e32 v73, v73, v243
	v_add_f32_e32 v74, v74, v244
	v_add_f32_e32 v75, v75, v245
	v_add_f32_e32 v76, v76, v246
	v_add_f32_e32 v77, v77, v247
	v_add_f32_e32 v78, v78, v248
	v_add_f32_e32 v79, v79, v249
	v_add_f32_e32 v96, v96, v250
	v_add_f32_e32 v97, v97, v251
	v_add_f32_e32 v98, v98, v252
	v_add_f32_e32 v99, v99, v253
	v_add_f32_e32 v100, v100, v188
	v_add_f32_e32 v101, v101, v189
	v_add_f32_e32 v102, v102, v190
	v_add_f32_e32 v103, v103, v191
	v_add_f32_e32 v104, v104, v192
	v_add_f32_e32 v105, v105, v193
	v_add_f32_e32 v106, v106, v194
	v_add_f32_e32 v107, v107, v195
	v_add_f32_e32 v108, v108, v196
	v_add_f32_e32 v109, v109, v197
	v_add_f32_e32 v110, v110, v198
	v_add_f32_e32 v111, v111, v199
	s_branch .LBB0_518

; __device__ __forceinline__ void attn_unit(LAS unsigned char* lds, const bf16_t* __restrict__ U3, const bf16_t* __restrict__ VT, bf16_t* __restrict__ MIX, ...
;     ...
;         if (t == 0 || __any(!(ssum <= 8192.0f))) {
;             if (t != 0) ATT_SCORES();
.LBB0_520:
	s_not_b64 s[16:17], s[26:27]
	s_andn2_b64 vcc, exec, s[26:27]
	s_mov_b64 s[26:27], -1
	s_cbranch_vccnz .LBB0_525
	s_mov_b32 s26, 0x46000000
	v_cmp_nge_f32_e32 vcc, s26, v186
	s_cbranch_vccz .LBB0_535
	ds_read_b128 v[96:99], v182
	ds_read_b128 v[100:103], v182 offset:8192
	ds_read_b128 v[104:107], v183
	ds_read_b128 v[108:111], v183 offset:8192
	ds_read_b128 v[188:191], v184
	ds_read_b128 v[192:195], v184 offset:8192
	ds_read_b128 v[196:199], v185
	ds_read_b128 v[182:185], v185 offset:8192
	s_setprio 1
	s_waitcnt lgkmcnt(0)
	v_mfma_f32_32x32x16_bf16 v[64:79], v[96:99], v[112:115], v[80:95]
	v_mfma_f32_32x32x16_bf16 v[80:95], v[100:103], v[112:115], v[80:95]
	v_mfma_f32_32x32x16_bf16 v[64:79], v[104:107], v[116:119], v[64:79]
	v_mfma_f32_32x32x16_bf16 v[80:95], v[108:111], v[116:119], v[80:95]
	v_mfma_f32_32x32x16_bf16 v[64:79], v[188:191], v[120:123], v[64:79]
	v_mfma_f32_32x32x16_bf16 v[80:95], v[192:195], v[120:123], v[80:95]
	v_mfma_f32_32x32x16_bf16 v[64:79], v[196:199], v[124:127], v[64:79]
	v_mfma_f32_32x32x16_bf16 v[80:95], v[182:185], v[124:127], v[80:95]
	s_setprio 0
	s_and_b64 vcc, exec, s[14:15]
	s_cbranch_vccnz .LBB0_524
	v_or_b32_e32 v96, s56, v157
	v_sub_u32_e32 v96, v96, v168
	v_max_i32_e32 v96, 0xfffffee0, v96
	v_min_i32_e32 v96, 0xa8, v96
	s_add_i32 s98, s79, 0x480
	v_lshl_add_u32 v96, v96, 2, s98
	s_and_b64 vcc, exec, s[10:11]
	s_cbranch_vccnz .Latt_slow_mt_b
	ds_read2_b32 v[234:235], v96 offset1:1
	ds_read2_b32 v[236:237], v96 offset0:2 offset1:3
	ds_read2_b32 v[238:239], v96 offset0:4 offset1:5
	ds_read2_b32 v[240:241], v96 offset0:6 offset1:7
	ds_read2_b32 v[242:243], v96 offset0:16 offset1:17
	ds_read2_b32 v[244:245], v96 offset0:18 offset1:19
	ds_read2_b32 v[246:247], v96 offset0:20 offset1:21
	ds_read2_b32 v[248:249], v96 offset0:22 offset1:23
	ds_read2_b32 v[250:251], v96 offset0:32 offset1:33
	ds_read2_b32 v[252:253], v96 offset0:34 offset1:35
	ds_read2_b32 v[188:189], v96 offset0:36 offset1:37
	ds_read2_b32 v[190:191], v96 offset0:38 offset1:39
	ds_read2_b32 v[192:193], v96 offset0:48 offset1:49
	ds_read2_b32 v[194:195], v96 offset0:50 offset1:51
	ds_read2_b32 v[196:197], v96 offset0:52 offset1:53
	ds_read2_b32 v[198:199], v96 offset0:54 offset1:55
	s_waitcnt lgkmcnt(0)
	v_add_f32_e32 v64, v64, v234
	v_add_f32_e32 v65, v65, v235
	v_add_f32_e32 v66, v66, v236
	v_add_f32_e32 v67, v67, v237
	v_add_f32_e32 v68, v68, v238
	v_add_f32_e32 v69, v69, v239
	v_add_f32_e32 v70, v70, v240
	v_add_f32_e32 v71, v71, v241
	v_add_f32_e32 v72, v72, v242
	v_add_f32_e32 v73, v73, v243
	v_add_f32_e32 v74, v74, v244
	v_add_f32_e32 v75, v75, v245
	v_add_f32_e32 v76, v76, v246
	v_add_f32_e32 v77, v77, v247
	v_add_f32_e32 v78, v78, v248
	v_add_f32_e32 v79, v79, v249
	v_add_f32_e32 v80, v80, v250
	v_add_f32_e32 v81, v81, v251
	v_add_f32_e32 v82, v82, v252
	v_add_f32_e32 v83, v83, v253
	v_add_f32_e32 v84, v84, v188
	v_add_f32_e32 v85, v85, v189
	v_add_f32_e32 v86, v86, v190
	v_add_f32_e32 v87, v87, v191
	v_add_f32_e32 v88, v88, v192
	v_add_f32_e32 v89, v89, v193
	v_add_f32_e32 v90, v90, v194
	v_add_f32_e32 v91, v91, v195
	v_add_f32_e32 v92, v92, v196
	v_add_f32_e32 v93, v93, v197
	v_add_f32_e32 v94, v94, v198
	v_add_f32_e32 v95, v95, v199
	s_branch .LBB0_524

; __device__ __forceinline__ void attn_unit(LAS unsigned char* lds, const bf16_t* __restrict__ U3, const bf16_t* __restrict__ VT, bf16_t* __restrict__ MIX, ...
;     ...
;             float rma = __builtin_fmaxf(__builtin_fmaxf(p0[0], p0[1]), p1[0]), rmb = __builtin_fmaxf(__builtin_fmaxf(p0[2], p0[3]), p1[1]);
;             rma = __builtin_fmaxf(__builtin_fmaxf(rma, p1[2]), p1[3]);
; #pragma unroll
;             for (int r = 4; r < 16; r += 4) { rma = __builtin_fmaxf(__builtin_fmaxf(rma, p0[r]), p0[r + 1]); rmb = __builtin_fmaxf(__builtin_fmaxf(rmb, p0[r + 2]), p0[r + 3]);
;                 rma = __builtin_fmaxf(__builtin_fmaxf(rma, p1[r]), p1[r + 1]); rmb = __builtin_fmaxf(__builtin_fmaxf(rmb, p1[r + 2]), p1[r + 3]); }
;             float rm = __builtin_fmaxf(rma, rmb);
;             { auto rr = __builtin_amdgcn_permlane32_swap(__float_as_uint(rm), __float_as_uint(rm), false, false); rm = __builtin_fmaxf(__uint_as_float(rr[0]), __uint_as_float(rr[1])); }
;             const float dl = (t == 0) ? rm : fmaxf(rm, 0.f); mhat += dl;
;             if (t != 0) { const float fsc = __builtin_amdgcn_exp2f(-dl); l *= fsc;
; #pragma unroll
;                 for (int d0 = 0; d0 < 4; ++d0)
; #pragma unroll
;                     for (int r = 0; r < 16; ++r) o[d0][r] *= fsc; }
.LBB0_526:
	s_mov_b32 s99, -1
	v_max_f32_e32 v80, v65, v65
	v_max_f32_e32 v81, v64, v64
	v_max_f32_e32 v80, v81, v80
	v_max3_f32 v81, v66, v67, v97
	v_max3_f32 v80, v80, v96, v98
	v_max3_f32 v80, v80, v99, v68
	v_max3_f32 v81, v81, v70, v71
	v_max3_f32 v80, v80, v69, v100
	v_max3_f32 v81, v81, v102, v103
	v_max3_f32 v80, v80, v101, v72
	v_max3_f32 v81, v81, v74, v75
	v_max3_f32 v80, v80, v73, v104
	v_max3_f32 v81, v81, v106, v107
	v_max3_f32 v80, v80, v105, v76
	v_max3_f32 v81, v81, v78, v79
	v_max3_f32 v80, v80, v77, v108
	v_max3_f32 v81, v81, v110, v111
	v_max3_f32 v80, v80, v109, v81
	v_mov_b32_e32 v81, v80
	s_nop 1
	v_permlane32_swap_b32_e32 v80, v81
	v_max_f32_e32 v81, v81, v81
	v_max_f32_e32 v80, v80, v80
	v_max_f32_e32 v80, v80, v81
	s_and_b64 vcc, exec, s[16:17]
	v_max_f32_e32 v81, 0, v80
	s_cbranch_vccnz .LBB0_528
	v_exp_f32_e64 v82, -v81
	s_nop 0
	v_pk_mul_f32 v[62:63], v[62:63], v[82:83] op_sel_hi:[1,0]
	v_pk_mul_f32 v[60:61], v[60:61], v[82:83] op_sel_hi:[1,0]
	v_pk_mul_f32 v[58:59], v[58:59], v[82:83] op_sel_hi:[1,0]
	v_pk_mul_f32 v[56:57], v[56:57], v[82:83] op_sel_hi:[1,0]
	v_pk_mul_f32 v[54:55], v[54:55], v[82:83] op_sel_hi:[1,0]
	v_pk_mul_f32 v[52:53], v[52:53], v[82:83] op_sel_hi:[1,0]
	v_pk_mul_f32 v[50:51], v[50:51], v[82:83] op_sel_hi:[1,0]
	v_pk_mul_f32 v[48:49], v[48:49], v[82:83] op_sel_hi:[1,0]
	v_pk_mul_f32 v[46:47], v[46:47], v[82:83] op_sel_hi:[1,0]
	v_pk_mul_f32 v[44:45], v[44:45], v[82:83] op_sel_hi:[1,0]
	v_pk_mul_f32 v[42:43], v[42:43], v[82:83] op_sel_hi:[1,0]
	v_pk_mul_f32 v[40:41], v[40:41], v[82:83] op_sel_hi:[1,0]
	v_pk_mul_f32 v[38:39], v[38:39], v[82:83] op_sel_hi:[1,0]
	v_pk_mul_f32 v[36:37], v[36:37], v[82:83] op_sel_hi:[1,0]
	v_pk_mul_f32 v[34:35], v[34:35], v[82:83] op_sel_hi:[1,0]
	v_pk_mul_f32 v[32:33], v[32:33], v[82:83] op_sel_hi:[1,0]
	v_pk_mul_f32 v[30:31], v[30:31], v[82:83] op_sel_hi:[1,0]
	v_pk_mul_f32 v[28:29], v[28:29], v[82:83] op_sel_hi:[1,0]
	v_pk_mul_f32 v[26:27], v[26:27], v[82:83] op_sel_hi:[1,0]
	v_pk_mul_f32 v[24:25], v[24:25], v[82:83] op_sel_hi:[1,0]
	v_pk_mul_f32 v[22:23], v[22:23], v[82:83] op_sel_hi:[1,0]
	v_pk_mul_f32 v[20:21], v[20:21], v[82:83] op_sel_hi:[1,0]
	v_pk_mul_f32 v[18:19], v[18:19], v[82:83] op_sel_hi:[1,0]
	v_pk_mul_f32 v[16:17], v[16:17], v[82:83] op_sel_hi:[1,0]
	v_pk_mul_f32 v[14:15], v[14:15], v[82:83] op_sel_hi:[1,0]
	v_pk_mul_f32 v[12:13], v[12:13], v[82:83] op_sel_hi:[1,0]
	v_pk_mul_f32 v[10:11], v[10:11], v[82:83] op_sel_hi:[1,0]
	v_pk_mul_f32 v[8:9], v[8:9], v[82:83] op_sel_hi:[1,0]
	v_pk_mul_f32 v[6:7], v[6:7], v[82:83] op_sel_hi:[1,0]
	v_pk_mul_f32 v[4:5], v[4:5], v[82:83] op_sel_hi:[1,0]
	v_pk_mul_f32 v[2:3], v[2:3], v[82:83] op_sel_hi:[1,0]
	v_pk_mul_f32 v[0:1], v[0:1], v[82:83] op_sel_hi:[1,0]
	v_mul_f32_e32 v169, v169, v82
